# phase 5: half of the workgroups run their glr unit before the GEMM tiles (the other half after), so the bandwidth-bound glr reads no longer all coincide at the phase end
# speedup vs baseline: 1.0105x; 1.0013x over previous
.LBB0_1023:
	s_cmp_lt_i32 s94, 6
	s_cselect_b64 s[8:9], -1, 0
	s_and_b64 s[0:1], s[8:9], s[0:1]
	s_andn2_b64 vcc, exec, s[0:1]
	s_cbranch_vccnz .LBB0_1146
	s_bfe_u32 s98, s97, 0x10003
	s_nop 0
	v_writelane_b32 v255, s98, 43
	s_nop 3
.Lp5_top:
	v_readlane_b32 s98, v255, 43
	s_nop 3
	s_cmp_eq_u32 s98, 1
	s_cbranch_scc1 .Lp5_glr
	s_cmpk_lt_i32 s97, 0x700
	v_readfirstlane_b32 s30, v0
	s_movk_i32 s2, 0x800
	s_cselect_b64 s[4:5], -1, 0
	s_cmpk_gt_i32 s97, 0x6ff
	s_cbranch_scc1 .LBB0_1026
	s_ashr_i32 s0, s97, 31
	s_lshr_b32 s0, s0, 29
	s_add_i32 s0, s97, s0
	s_ashr_i32 s1, s0, 3
	s_and_b32 s0, s0, -8
	s_sub_i32 s0, s97, s0
	s_cmp_lt_i32 s0, 0
	s_movk_i32 s3, 0xe1
	s_cselect_b32 s3, s3, 0xe0
	s_mul_i32 s0, s3, s0
	s_add_i32 s0, s0, s1
	s_mul_hi_i32 s1, s0, 0x92492493
	s_add_i32 s1, s1, s0
	s_lshr_b32 s3, s1, 31
	s_ashr_i32 s1, s1, 7
	s_add_i32 s1, s1, s3
	s_lshl_b32 s3, s1, 3
	s_mulk_i32 s1, 0xe0
	s_sub_i32 s0, s0, s1
	s_sext_i32_i16 s1, s0
	s_bfe_u32 s1, s1, 0x3001c
	s_add_i32 s1, s0, s1
	s_sext_i32_i16 s6, s1
	s_and_b32 s1, s1, 0xfff8
	s_sub_i32 s0, s0, s1
	s_sext_i32_i16 s0, s0
	s_add_i32 s0, s3, s0
	s_ashr_i32 s55, s6, 3

.LBB0_1137:
	v_readlane_b32 s98, v255, 43
	s_nop 3
	s_cmp_eq_u32 s98, 2
	s_cbranch_scc1 .LBB0_1146

.Lglr_done:
	v_readlane_b32 s98, v255, 43
	s_nop 3
	s_cmp_eq_u32 s98, 1
	s_cbranch_scc0 .LBB0_1146
	s_mov_b32 s98, 2
	s_nop 0
	v_writelane_b32 v255, s98, 43
	s_waitcnt vmcnt(0) lgkmcnt(0)
	s_barrier
	s_branch .Lp5_top
